# attention QK^T: all 8 K-fragment ds_reads issued up front into distinct registers, MFMA chain back-to-back with descending lgkmcnt
# baseline (speedup 1.0000x reference)
; #define LAS __attribute__((address_space(3)))
; __device__ __forceinline__ void unit(const Ctx& C, int xq, int idx, LAS unsigned char* lds) {
;     ...
;         f32x16 S0, S1;
; #pragma unroll
;         for (int r = 0; r < 16; ++r) { S0[r] = 0.f; S1[r] = 0.f; }
; #pragma unroll
;         for (int d0 = 0; d0 < 4; ++d0) {
;             const bf16x8 a0 = *(const LAS bf16x8*)(sb + koff + d0 * 32), a1 = *(const LAS bf16x8*)(sb + koff + 32 * 144 + d0 * 32);
;             S0 = __builtin_amdgcn_mfma_f32_32x32x16_bf16(a0, qf[d0], S0, 0, 0, 0);
;             S1 = __builtin_amdgcn_mfma_f32_32x32x16_bf16(a1, qf[d0], S1, 0, 0, 0);
;         }
;         if (j + 3 <= cw) {
; #pragma unroll
;             for (int r = 0; r < 16; ++r) { float a_ = __builtin_fmaf(S0[r], C2, b15), b_ = __builtin_fmaf(S1[r], C2, b15); asm("" : "+v"(a_)); asm("" : "+v"(b_)); S0[r] = a_; S1[r] = b_; }
.LBB0_515:
	s_add_i32 s93, s92, -4
	s_cmp_le_u32 s93, s86
	s_cselect_b64 s[34:35], -1, 0
	s_and_b64 s[34:35], s[42:43], s[34:35]
	s_andn2_b64 vcc, exec, s[34:35]
	s_cbranch_vccnz .LBB0_523
	v_add_u32_e32 v76, 0, v193
	ds_read_b128 v[64:67], v76
	ds_read_b128 v[80:83], v76 offset:4608
	ds_read_b128 v[68:71], v76 offset:32
	ds_read_b128 v[72:75], v76 offset:4640
	ds_read_b128 v[84:87], v76 offset:64
	ds_read_b128 v[88:91], v76 offset:4672
	ds_read_b128 v[92:95], v76 offset:96
	ds_read_b128 v[222:225], v76 offset:4704
	s_add_i32 s4, s92, -1
	s_mov_b64 s[56:57], -1
	s_cmp_gt_u32 s4, s86
	s_waitcnt lgkmcnt(7)
	v_mfma_f32_32x32x16_bf16 v[112:127], v[64:67], v[128:131], 0
	s_waitcnt lgkmcnt(6)
	v_mfma_f32_32x32x16_bf16 v[96:111], v[80:83], v[128:131], 0
	s_waitcnt lgkmcnt(5)
	v_mfma_f32_32x32x16_bf16 v[112:127], v[68:71], v[132:135], v[112:127]
	s_waitcnt lgkmcnt(4)
	v_mfma_f32_32x32x16_bf16 v[96:111], v[72:75], v[132:135], v[96:111]
	s_waitcnt lgkmcnt(3)
	v_mfma_f32_32x32x16_bf16 v[112:127], v[84:87], v[136:139], v[112:127]
	s_waitcnt lgkmcnt(2)
	v_mfma_f32_32x32x16_bf16 v[96:111], v[88:91], v[136:139], v[96:111]
	s_waitcnt lgkmcnt(1)
	v_mfma_f32_32x32x16_bf16 v[112:127], v[92:95], v[140:143], v[112:127]
	s_waitcnt lgkmcnt(0)
	v_mfma_f32_32x32x16_bf16 v[96:111], v[222:225], v[140:143], v[96:111]
	s_cbranch_scc1 .LBB0_518
	s_nop 8
	v_fmamk_f32 v80, v112, 0x3e38aa3b, v191
	s_nop 0
	v_fmamk_f32 v64, v96, 0x3e38aa3b, v191
	v_fmamk_f32 v81, v113, 0x3e38aa3b, v191
	v_fmamk_f32 v65, v97, 0x3e38aa3b, v191
	v_fmamk_f32 v82, v114, 0x3e38aa3b, v191
	v_fmamk_f32 v66, v98, 0x3e38aa3b, v191
	v_fmamk_f32 v83, v115, 0x3e38aa3b, v191
	v_fmamk_f32 v67, v99, 0x3e38aa3b, v191
	v_fmamk_f32 v84, v116, 0x3e38aa3b, v191
	v_fmamk_f32 v68, v100, 0x3e38aa3b, v191
	v_fmamk_f32 v85, v117, 0x3e38aa3b, v191
	v_fmamk_f32 v69, v101, 0x3e38aa3b, v191
	v_fmamk_f32 v86, v118, 0x3e38aa3b, v191
	v_fmamk_f32 v70, v102, 0x3e38aa3b, v191
	v_fmamk_f32 v87, v119, 0x3e38aa3b, v191
	v_fmamk_f32 v71, v103, 0x3e38aa3b, v191
	v_fmamk_f32 v88, v120, 0x3e38aa3b, v191
	v_fmamk_f32 v72, v104, 0x3e38aa3b, v191
	v_fmamk_f32 v89, v121, 0x3e38aa3b, v191
	v_fmamk_f32 v73, v105, 0x3e38aa3b, v191
	v_fmamk_f32 v90, v122, 0x3e38aa3b, v191
	v_fmamk_f32 v74, v106, 0x3e38aa3b, v191
	v_fmamk_f32 v91, v123, 0x3e38aa3b, v191
	v_fmamk_f32 v75, v107, 0x3e38aa3b, v191
	v_fmamk_f32 v92, v124, 0x3e38aa3b, v191
	v_fmamk_f32 v76, v108, 0x3e38aa3b, v191
	v_fmamk_f32 v93, v125, 0x3e38aa3b, v191
	v_fmamk_f32 v77, v109, 0x3e38aa3b, v191
	v_fmamk_f32 v94, v126, 0x3e38aa3b, v191
	v_fmamk_f32 v78, v110, 0x3e38aa3b, v191
	v_fmamk_f32 v95, v127, 0x3e38aa3b, v191
	v_fmamk_f32 v79, v111, 0x3e38aa3b, v191
	s_mov_b64 s[56:57], 0

; #define LAS __attribute__((address_space(3)))
; __device__ __forceinline__ void unit(const Ctx& C, int xq, int idx, LAS unsigned char* lds) {
;     ...
;         f32x16 S0, S1;
; #pragma unroll
;         for (int r = 0; r < 16; ++r) { S0[r] = 0.f; S1[r] = 0.f; }
; #pragma unroll
;         for (int d0 = 0; d0 < 4; ++d0) {
;             const bf16x8 a0 = *(const LAS bf16x8*)(sb + koff + d0 * 32), a1 = *(const LAS bf16x8*)(sb + koff + 32 * 144 + d0 * 32);
;             S0 = __builtin_amdgcn_mfma_f32_32x32x16_bf16(a0, qf[d0], S0, 0, 0, 0);
;             S1 = __builtin_amdgcn_mfma_f32_32x32x16_bf16(a1, qf[d0], S1, 0, 0, 0);
;         }
;         if (j + 3 <= cw) {
; #pragma unroll
;             for (int r = 0; r < 16; ++r) { float a_ = __builtin_fmaf(S0[r], C2, b15), b_ = __builtin_fmaf(S1[r], C2, b15); asm("" : "+v"(a_)); asm("" : "+v"(b_)); S0[r] = a_; S1[r] = b_; }
.LBB0_537:
	v_add_u32_e32 v76, 0, v193
	ds_read_b128 v[64:67], v76 offset:36864
	ds_read_b128 v[80:83], v76 offset:41472
	ds_read_b128 v[68:71], v76 offset:36896
	ds_read_b128 v[72:75], v76 offset:41504
	ds_read_b128 v[84:87], v76 offset:36928
	ds_read_b128 v[88:91], v76 offset:41536
	ds_read_b128 v[92:95], v76 offset:36960
	ds_read_b128 v[222:225], v76 offset:41568
	s_cmp_gt_u32 s92, s86
	s_waitcnt lgkmcnt(7)
	v_mfma_f32_32x32x16_bf16 v[112:127], v[64:67], v[128:131], 0
	s_waitcnt lgkmcnt(6)
	v_mfma_f32_32x32x16_bf16 v[96:111], v[80:83], v[128:131], 0
	s_waitcnt lgkmcnt(5)
	v_mfma_f32_32x32x16_bf16 v[112:127], v[68:71], v[132:135], v[112:127]
	s_waitcnt lgkmcnt(4)
	v_mfma_f32_32x32x16_bf16 v[96:111], v[72:75], v[132:135], v[96:111]
	s_waitcnt lgkmcnt(3)
	v_mfma_f32_32x32x16_bf16 v[112:127], v[84:87], v[136:139], v[112:127]
	s_waitcnt lgkmcnt(2)
	v_mfma_f32_32x32x16_bf16 v[96:111], v[88:91], v[136:139], v[96:111]
	s_waitcnt lgkmcnt(1)
	v_mfma_f32_32x32x16_bf16 v[112:127], v[92:95], v[140:143], v[112:127]
	s_waitcnt lgkmcnt(0)
	v_mfma_f32_32x32x16_bf16 v[96:111], v[222:225], v[140:143], v[96:111]
	s_cbranch_scc1 .LBB0_539
	s_nop 8
	v_fmamk_f32 v80, v112, 0x3e38aa3b, v191
	s_nop 0
	v_fmamk_f32 v64, v96, 0x3e38aa3b, v191
	v_fmamk_f32 v81, v113, 0x3e38aa3b, v191
	v_fmamk_f32 v65, v97, 0x3e38aa3b, v191
	v_fmamk_f32 v82, v114, 0x3e38aa3b, v191
	v_fmamk_f32 v66, v98, 0x3e38aa3b, v191
	v_fmamk_f32 v83, v115, 0x3e38aa3b, v191
	v_fmamk_f32 v67, v99, 0x3e38aa3b, v191
	v_fmamk_f32 v84, v116, 0x3e38aa3b, v191
	v_fmamk_f32 v68, v100, 0x3e38aa3b, v191
	v_fmamk_f32 v85, v117, 0x3e38aa3b, v191
	v_fmamk_f32 v69, v101, 0x3e38aa3b, v191
	v_fmamk_f32 v86, v118, 0x3e38aa3b, v191
	v_fmamk_f32 v70, v102, 0x3e38aa3b, v191
	v_fmamk_f32 v87, v119, 0x3e38aa3b, v191
	v_fmamk_f32 v71, v103, 0x3e38aa3b, v191
	v_fmamk_f32 v88, v120, 0x3e38aa3b, v191
	v_fmamk_f32 v72, v104, 0x3e38aa3b, v191
	v_fmamk_f32 v89, v121, 0x3e38aa3b, v191
	v_fmamk_f32 v73, v105, 0x3e38aa3b, v191
	v_fmamk_f32 v90, v122, 0x3e38aa3b, v191
	v_fmamk_f32 v74, v106, 0x3e38aa3b, v191
	v_fmamk_f32 v91, v123, 0x3e38aa3b, v191
	v_fmamk_f32 v75, v107, 0x3e38aa3b, v191
	v_fmamk_f32 v92, v124, 0x3e38aa3b, v191
	v_fmamk_f32 v76, v108, 0x3e38aa3b, v191
	v_fmamk_f32 v93, v125, 0x3e38aa3b, v191
	v_fmamk_f32 v77, v109, 0x3e38aa3b, v191
	v_fmamk_f32 v94, v126, 0x3e38aa3b, v191
	v_fmamk_f32 v78, v110, 0x3e38aa3b, v191
	v_fmamk_f32 v95, v127, 0x3e38aa3b, v191
	v_fmamk_f32 v79, v111, 0x3e38aa3b, v191
	s_mov_b64 s[56:57], 0
